# v049 with rank reversal applied to NSA quarters 1 and 2 only (quarter 3 forward) to rebalance ranks under the unrotated item order
# baseline (speedup 1.0000x reference)
; __device__ __forceinline__ void attention_phase(const Ctx& C) {
;     const int bxx = C.gw / NWAVES; const bool xmode = (C.G & 7) == 0;
;     const int x = bxx & 7, rank = xmode ? (bxx >> 3) * NWAVES + C.wave : C.gw, nrank = xmode ? (C.G >> 3) * NWAVES : C.NGW, nitem = xmode ? 1536 : 12288;
;     const int nper = (nitem + nrank - 1) / nrank, nmem_it = xmode ? (512 + nrank - 1) / nrank : 0; const bool flip = xmode && (nitem % nrank == 0); const int rot = flip ? ((C.wave * 3) >> 3) * 2 : 0;
;     for (int k0 = 0; k0 < nper; ++k0) {
;         const int kk = flip ? (k0 + rot) % nper : k0; const int i = rank + kk * nrank; if (i >= nitem) continue;
;         int nsa_n, mem_e;
;         if (xmode) { nsa_n = (i < 1024) ? (x >> 1) * 2048 + 2 * i + (x & 1) : -1; mem_e = x * 512 + (i - 1024); }
;         else { if (i < 8192) { const int k = i >> 11, w = i & 2047; nsa_n = k * 2048 + ((k & 1) ? 2047 - w : w); } else nsa_n = -1; mem_e = i - 8192; }
;         if (nsa_n >= 0) { const int k = nsa_n >> 11; nsa_tile(C, k >> 1, k & 1, (nsa_n & 2047) * 8); }
.LBB0_653:
	s_mul_i32 s3, s0, s26
	s_sub_i32 s2, s26, s9
	s_add_i32 s2, s2, -1
	s_sub_i32 s1, s0, 1
	s_cmp_lt_u32 s1, 2
	s_cselect_b32 s2, s2, s9
	s_add_i32 s3, s3, s2
	s_cmp_ge_i32 s3, s47
	s_cbranch_scc1 .LBB0_650
	s_mov_b64 s[0:1], -1
	s_and_b64 vcc, exec, s[50:51]
	s_cbranch_vccz .LBB0_661
	s_and_b32 s0, s3, 0x7ff
	s_and_b32 s1, s3, 0xfffff800
	s_and_b32 s2, s3, 0x800
	s_xor_b32 s4, s0, 0x7ff
	s_cmp_eq_u32 s2, 0
	s_cselect_b32 s0, s0, s4
	s_or_b32 s0, s0, s1
	s_cmpk_lt_i32 s3, 0x2000
	s_cselect_b32 s2, s0, -1
	s_add_i32 s5, s3, 0xffffe000
	s_cbranch_execz .LBB0_662
